# adds G5 peeled first K-tile, 1us G1 skew steps, own PART loads default cache policy
# speedup vs baseline: 1.0212x; 1.0008x over previous
.Lskew_loop_g1:
	s_sleep 32
	s_sub_u32 s4, s4, 1
	s_cmp_lg_u32 s4, 0
	s_cbranch_scc1 .Lskew_loop_g1

.LBB0_932:
	v_add_u32_e32 v64, s96, v133
	v_lshl_add_u32 v144, v64, 1, v64
	v_add_u32_e32 v138, 1, v144
	v_lshlrev_b64 v[64:65], 8, v[138:139]
	v_add_u32_e32 v138, 49, v144
	v_lshl_add_u64 v[64:65], v[140:141], 0, v[64:65]
	v_lshlrev_b64 v[66:67], 8, v[138:139]
	v_add_u32_e32 v138, 2, v144
	v_lshl_add_u64 v[66:67], v[140:141], 0, v[66:67]
	global_load_dwordx4 v[120:123], v[64:65], off
	global_load_dwordx4 v[112:115], v[64:65], off offset:64
	global_load_dwordx4 v[124:127], v[66:67], off
	global_load_dwordx4 v[116:119], v[66:67], off offset:64
	global_load_dwordx4 v[104:107], v[64:65], off offset:128
	global_load_dwordx4 v[96:99], v[64:65], off offset:192
	global_load_dwordx4 v[108:111], v[66:67], off offset:128
	global_load_dwordx4 v[100:103], v[66:67], off offset:192
	v_lshlrev_b64 v[64:65], 8, v[138:139]
	v_add_u32_e32 v138, 50, v144
	v_lshlrev_b64 v[66:67], 8, v[138:139]
	v_lshl_add_u64 v[64:65], v[140:141], 0, v[64:65]
	v_lshl_add_u64 v[68:69], v[140:141], 0, v[66:67]
	global_load_dwordx4 v[88:91], v[64:65], off
	global_load_dwordx4 v[80:83], v[64:65], off offset:64
	global_load_dwordx4 v[92:95], v[68:69], off
	global_load_dwordx4 v[84:87], v[68:69], off offset:64
	global_load_dwordx4 v[72:75], v[64:65], off offset:128
	s_nop 0
	global_load_dwordx4 v[64:67], v[64:65], off offset:192
	s_nop 0
	global_load_dwordx4 v[76:79], v[68:69], off offset:128
	s_nop 0
	global_load_dwordx4 v[68:71], v[68:69], off offset:192
	ds_bpermute_b32 v161, v137, v159
	s_cmp_eq_u32 s97, 0
	s_cselect_b64 s[86:87], -1, 0
	s_and_b64 vcc, exec, s[86:87]
	v_add_u32_e32 v160, v135, v136
	s_cbranch_vccz .LBB0_935
	s_cmp_gt_u32 s97, 1
	s_cselect_b64 vcc, -1, 0
	s_cmp_lt_u32 s97, 2
	s_cbranch_scc0 .LBB0_936

.LBB0_935:
	v_add_u32_e32 v138, 48, v144
	v_mov_b32_e32 v145, v139
	v_lshlrev_b64 v[162:163], 8, v[138:139]
	v_lshlrev_b64 v[144:145], 8, v[144:145]
	v_lshl_add_u64 v[186:187], v[140:141], 0, v[162:163]
	v_lshl_add_u64 v[144:145], v[140:141], 0, v[144:145]
	global_load_dwordx4 v[162:165], v[144:145], off
	global_load_dwordx4 v[166:169], v[186:187], off
	global_load_dwordx4 v[170:173], v[144:145], off offset:64
	global_load_dwordx4 v[174:177], v[186:187], off offset:64
	global_load_dwordx4 v[178:181], v[144:145], off offset:128
	global_load_dwordx4 v[182:185], v[186:187], off offset:128
	s_nop 0
	global_load_dwordx4 v[186:189], v[186:187], off offset:192
	s_nop 0
	global_load_dwordx4 v[190:193], v[144:145], off offset:192
	s_waitcnt vmcnt(7)
	ds_write_b128 v160, v[162:165]
	s_waitcnt vmcnt(6)
	ds_write_b128 v157, v[166:169]
	s_waitcnt lgkmcnt(0)
	ds_read2_b64 v[162:165], v158 offset1:2
	ds_read2_b64 v[166:169], v158 offset0:4 offset1:6
	s_waitcnt lgkmcnt(0)
	s_waitcnt vmcnt(5)
	ds_write_b128 v160, v[170:173]
	s_waitcnt vmcnt(4)
	ds_write_b128 v157, v[174:177]
	s_waitcnt lgkmcnt(0)
	ds_read2_b64 v[170:173], v158 offset1:2
	ds_read2_b64 v[174:177], v158 offset0:4 offset1:6
	s_waitcnt lgkmcnt(0)
	s_waitcnt vmcnt(3)
	ds_write_b128 v160, v[178:181]
	s_waitcnt vmcnt(2)
	ds_write_b128 v157, v[182:185]
	s_waitcnt lgkmcnt(0)
	ds_read2_b64 v[178:181], v158 offset1:2
	s_waitcnt lgkmcnt(8)
	v_lshlrev_b32_e32 v138, 16, v162
	v_add_f32_e32 v48, v48, v138
	s_waitcnt lgkmcnt(4)
	v_lshlrev_b32_e32 v138, 16, v170
	v_add_f32_e32 v32, v32, v138
	s_waitcnt lgkmcnt(0)
	v_lshlrev_b32_e32 v138, 16, v178
	v_and_b32_e32 v144, 0xffff0000, v162
	v_lshlrev_b32_e32 v145, 16, v163
	v_and_b32_e32 v162, 0xffff0000, v163
	v_lshlrev_b32_e32 v163, 16, v164
	v_and_b32_e32 v164, 0xffff0000, v164
	v_lshlrev_b32_e32 v182, 16, v165
	v_and_b32_e32 v165, 0xffff0000, v165
	v_add_f32_e32 v16, v16, v138
	v_and_b32_e32 v138, 0xffff0000, v178
	v_add_f32_e32 v51, v51, v162
	v_add_f32_e32 v52, v52, v163
	v_add_f32_e32 v53, v53, v164
	v_add_f32_e32 v55, v55, v165
	v_and_b32_e32 v162, 0xffff0000, v171
	v_lshlrev_b32_e32 v163, 16, v172
	v_and_b32_e32 v164, 0xffff0000, v172
	v_lshlrev_b32_e32 v165, 16, v173
	v_add_f32_e32 v17, v17, v138
	v_lshlrev_b32_e32 v138, 16, v179
	v_add_f32_e32 v35, v35, v162
	v_add_f32_e32 v36, v36, v163
	v_add_f32_e32 v37, v37, v164
	v_add_f32_e32 v38, v38, v165
	ds_read2_b64 v[162:165], v158 offset0:4 offset1:6
	v_add_f32_e32 v18, v18, v138
	v_and_b32_e32 v138, 0xffff0000, v179
	v_add_f32_e32 v19, v19, v138
	v_lshlrev_b32_e32 v138, 16, v180
	v_add_f32_e32 v20, v20, v138
	v_and_b32_e32 v138, 0xffff0000, v180
	v_add_f32_e32 v21, v21, v138
	v_lshlrev_b32_e32 v138, 16, v181
	v_add_f32_e32 v22, v22, v138
	v_and_b32_e32 v138, 0xffff0000, v181
	v_add_f32_e32 v23, v23, v138
	s_waitcnt lgkmcnt(0)
	v_lshlrev_b32_e32 v138, 16, v162
	v_lshlrev_b32_e32 v183, 16, v166
	v_and_b32_e32 v166, 0xffff0000, v166
	v_lshlrev_b32_e32 v184, 16, v167
	v_and_b32_e32 v167, 0xffff0000, v167
	v_lshlrev_b32_e32 v185, 16, v168
	v_and_b32_e32 v168, 0xffff0000, v168
	v_lshlrev_b32_e32 v194, 16, v169
	v_and_b32_e32 v169, 0xffff0000, v169
	v_add_f32_e32 v24, v24, v138
	v_and_b32_e32 v138, 0xffff0000, v162
	s_waitcnt lgkmcnt(0)
	s_waitcnt vmcnt(0)
	ds_write_b128 v160, v[190:193]
	ds_write_b128 v157, v[186:189]
	v_add_f32_e32 v57, v57, v166
	v_add_f32_e32 v59, v59, v167
	v_add_f32_e32 v61, v61, v168
	v_add_f32_e32 v63, v63, v169
	v_and_b32_e32 v166, 0xffff0000, v173
	v_lshlrev_b32_e32 v167, 16, v174
	v_and_b32_e32 v168, 0xffff0000, v174
	v_lshlrev_b32_e32 v169, 16, v175
	v_add_f32_e32 v25, v25, v138
	v_lshlrev_b32_e32 v138, 16, v163
	s_waitcnt lgkmcnt(0)
	v_add_f32_e32 v39, v39, v166
	v_add_f32_e32 v40, v40, v167
	v_add_f32_e32 v41, v41, v168
	v_add_f32_e32 v42, v42, v169
	v_add_f32_e32 v26, v26, v138
	v_and_b32_e32 v138, 0xffff0000, v163
	ds_read2_b64 v[166:169], v158 offset1:2
	v_add_f32_e32 v27, v27, v138
	v_lshlrev_b32_e32 v138, 16, v164
	v_add_f32_e32 v28, v28, v138
	v_and_b32_e32 v138, 0xffff0000, v164
	v_add_f32_e32 v29, v29, v138
	v_lshlrev_b32_e32 v138, 16, v165
	v_add_f32_e32 v30, v30, v138
	v_and_b32_e32 v138, 0xffff0000, v165
	v_add_f32_e32 v31, v31, v138
	s_waitcnt lgkmcnt(0)
	v_lshlrev_b32_e32 v138, 16, v166
	v_add_f32_e32 v0, v0, v138
	v_and_b32_e32 v138, 0xffff0000, v166
	v_add_f32_e32 v1, v1, v138
	v_lshlrev_b32_e32 v138, 16, v167
	ds_read2_b64 v[162:165], v158 offset0:4 offset1:6
	v_add_f32_e32 v2, v2, v138
	v_and_b32_e32 v138, 0xffff0000, v167
	v_add_f32_e32 v3, v3, v138
	v_lshlrev_b32_e32 v138, 16, v168
	v_add_f32_e32 v4, v4, v138
	v_and_b32_e32 v138, 0xffff0000, v168
	v_add_f32_e32 v5, v5, v138
	v_lshlrev_b32_e32 v138, 16, v169
	v_add_f32_e32 v6, v6, v138
	v_and_b32_e32 v138, 0xffff0000, v169
	v_add_f32_e32 v7, v7, v138
	s_waitcnt lgkmcnt(0)
	v_lshlrev_b32_e32 v138, 16, v162
	v_add_f32_e32 v8, v8, v138
	v_and_b32_e32 v138, 0xffff0000, v162
	v_add_f32_e32 v9, v9, v138
	v_lshlrev_b32_e32 v138, 16, v163
	v_add_f32_e32 v10, v10, v138
	v_and_b32_e32 v138, 0xffff0000, v163
	v_add_f32_e32 v11, v11, v138
	v_lshlrev_b32_e32 v138, 16, v164
	v_add_f32_e32 v12, v12, v138
	v_and_b32_e32 v138, 0xffff0000, v164
	v_add_f32_e32 v13, v13, v138
	v_lshlrev_b32_e32 v138, 16, v165
	s_waitcnt lgkmcnt(0)
	v_add_f32_e32 v49, v49, v144
	v_add_f32_e32 v50, v50, v145
	v_and_b32_e32 v144, 0xffff0000, v170
	v_lshlrev_b32_e32 v145, 16, v171
	v_and_b32_e32 v170, 0xffff0000, v175
	v_lshlrev_b32_e32 v171, 16, v176
	v_and_b32_e32 v172, 0xffff0000, v176
	v_lshlrev_b32_e32 v173, 16, v177
	v_and_b32_e32 v174, 0xffff0000, v177
	v_add_f32_e32 v14, v14, v138
	v_and_b32_e32 v138, 0xffff0000, v165
	v_add_f32_e32 v54, v54, v182
	v_add_f32_e32 v56, v56, v183
	v_add_f32_e32 v58, v58, v184
	v_add_f32_e32 v60, v60, v185
	v_add_f32_e32 v62, v62, v194
	v_add_f32_e32 v33, v33, v144
	v_add_f32_e32 v34, v34, v145
	v_add_f32_e32 v43, v43, v170
	v_add_f32_e32 v44, v44, v171
	v_add_f32_e32 v45, v45, v172
	v_add_f32_e32 v46, v46, v173
	v_add_f32_e32 v47, v47, v174
	v_add_f32_e32 v15, v15, v138
	s_cmp_gt_u32 s97, 1
	s_cselect_b64 vcc, -1, 0
	s_cmp_lt_u32 s97, 2
	s_cbranch_scc1 .LBB0_934

.LBB0_1253:
	s_lshl_b32 s5, s54, 12
	v_mbcnt_lo_u32_b32 v0, -1, 0
	v_mbcnt_hi_u32_b32 v0, -1, v0
	s_add_i32 s5, s5, s69
	v_and_b32_e32 v2, 15, v0
	v_lshlrev_b32_e32 v1, 4, v0
	v_and_b32_e32 v1, 0xffffff00, v1
	v_lshl_or_b32 v3, v2, 4, s5
	v_add_u32_e32 v1, v3, v1
	v_add_u32_e32 v3, 0x800, v1
	global_load_dwordx4 v[8:11], v1, s[20:21]
	global_load_dwordx4 v[4:7], v3, s[20:21]
	v_and_b32_e32 v0, -16, v0
	v_add_u32_e32 v3, s70, v0
	v_ashrrev_i32_e32 v12, 7, v3
	v_cmp_lt_i32_e32 vcc, 2, v12
	v_mov_b64_e32 v[0:1], s[8:9]
	s_and_saveexec_b64 s[50:51], vcc
	s_xor_b64 s[50:51], exec, s[50:51]
	s_lshl_b32 s5, s4, 7
	v_mov_b64_e32 v[0:1], s[10:11]
	s_or_saveexec_b64 s[50:51], s[50:51]
	v_mov_b32_e32 v13, s5
	s_xor_b64 exec, exec, s[50:51]
	v_mul_lo_u32 v12, v12, s77
	v_lshl_add_u32 v13, s4, 7, v12
	s_or_b64 exec, exec, s[50:51]
	v_and_b32_e32 v3, 0x70, v3
	v_or3_b32 v2, v3, v13, v2
	v_ashrrev_i32_e32 v3, 31, v2
	v_lshl_add_u64 v[0:1], v[2:3], 2, v[0:1]
	global_load_dword v136, v[0:1], off
	s_ashr_i32 s37, s36, 31
	s_lshl_b64 s[50:51], s[36:37], 19
	s_cmp_eq_u32 s82, 0
	s_cselect_b32 s37, s48, 0
	s_cselect_b32 s5, s49, 0
	s_cselect_b32 s55, s44, 0
	s_cselect_b32 s84, s45, 0
	s_add_u32 s50, s37, s50
	s_addc_u32 s51, s5, s51
	s_and_b64 s[52:53], s[60:61], exec
	s_cselect_b32 s5, s51, s57
	s_cselect_b32 s37, s50, s56
	s_ashr_i32 s39, s38, 31
	s_lshl_b64 s[52:53], s[38:39], 19
	s_add_u32 s52, s55, s52
	s_addc_u32 s53, s84, s53
	s_and_b64 s[60:61], s[60:61], exec
	s_cselect_b32 s39, s53, s59
	s_cselect_b32 s55, s52, s58
	s_add_u32 s56, s56, 0x40080
	s_addc_u32 s57, s57, 0
	s_add_u32 s84, s58, 0x100
	s_addc_u32 s85, s59, 0
	s_mov_b32 s86, -2
	s_cmp_lg_u32 s65, 0
	s_cbranch_scc1 .Lg5_peel
	v_mov_b32_e32 v0, 0
	v_mov_b32_e32 v1, v0
	v_mov_b32_e32 v2, v0
	v_mov_b32_e32 v3, v0
	v_mov_b32_e32 v44, v0
	v_mov_b32_e32 v45, v0
	v_mov_b32_e32 v46, v0
	v_mov_b32_e32 v47, v0
	v_mov_b32_e32 v48, v0
	v_mov_b32_e32 v49, v0
	v_mov_b32_e32 v50, v0
	v_mov_b32_e32 v51, v0
	v_mov_b32_e32 v52, v0
	v_mov_b32_e32 v53, v0
	v_mov_b32_e32 v54, v0
	v_mov_b32_e32 v55, v0
	v_mov_b32_e32 v56, v0
	v_mov_b32_e32 v57, v0
	v_mov_b32_e32 v58, v0
	v_mov_b32_e32 v59, v0
	v_mov_b32_e32 v60, v0
	v_mov_b32_e32 v61, v0
	v_mov_b32_e32 v62, v0
	v_mov_b32_e32 v63, v0
	v_mov_b32_e32 v72, v0
	v_mov_b32_e32 v73, v0
	v_mov_b32_e32 v74, v0
	v_mov_b32_e32 v75, v0
	v_mov_b32_e32 v76, v0
	v_mov_b32_e32 v77, v0
	v_mov_b32_e32 v78, v0
	v_mov_b32_e32 v79, v0
	v_mov_b32_e32 v20, v0
	v_mov_b32_e32 v21, v0
	v_mov_b32_e32 v22, v0
	v_mov_b32_e32 v23, v0
	v_mov_b32_e32 v24, v0
	v_mov_b32_e32 v25, v0
	v_mov_b32_e32 v26, v0
	v_mov_b32_e32 v27, v0
	v_mov_b32_e32 v64, v0
	v_mov_b32_e32 v65, v0
	v_mov_b32_e32 v66, v0
	v_mov_b32_e32 v67, v0
	v_mov_b32_e32 v68, v0
	v_mov_b32_e32 v69, v0
	v_mov_b32_e32 v70, v0
	v_mov_b32_e32 v71, v0
	v_mov_b32_e32 v80, v0
	v_mov_b32_e32 v81, v0
	v_mov_b32_e32 v82, v0
	v_mov_b32_e32 v83, v0
	v_mov_b32_e32 v84, v0
	v_mov_b32_e32 v85, v0
	v_mov_b32_e32 v86, v0
	v_mov_b32_e32 v87, v0
	v_mov_b32_e32 v88, v0
	v_mov_b32_e32 v89, v0
	v_mov_b32_e32 v90, v0
	v_mov_b32_e32 v91, v0
	v_mov_b32_e32 v92, v0
	v_mov_b32_e32 v93, v0
	v_mov_b32_e32 v94, v0
	v_mov_b32_e32 v95, v0
	v_mov_b32_e32 v96, v0
	v_mov_b32_e32 v97, v0
	v_mov_b32_e32 v98, v0
	v_mov_b32_e32 v99, v0
	v_mov_b32_e32 v100, v0
	v_mov_b32_e32 v101, v0
	v_mov_b32_e32 v102, v0
	v_mov_b32_e32 v103, v0
	v_mov_b32_e32 v104, v0
	v_mov_b32_e32 v105, v0
	v_mov_b32_e32 v106, v0
	v_mov_b32_e32 v107, v0
	v_mov_b32_e32 v108, v0
	v_mov_b32_e32 v109, v0
	v_mov_b32_e32 v110, v0
	v_mov_b32_e32 v111, v0
	v_mov_b32_e32 v112, v0
	v_mov_b32_e32 v113, v0
	v_mov_b32_e32 v114, v0
	v_mov_b32_e32 v115, v0
	v_mov_b32_e32 v116, v0
	v_mov_b32_e32 v117, v0
	v_mov_b32_e32 v118, v0
	v_mov_b32_e32 v119, v0
	v_mov_b32_e32 v12, v0
	v_mov_b32_e32 v13, v0
	v_mov_b32_e32 v14, v0
	v_mov_b32_e32 v15, v0
	v_mov_b32_e32 v16, v0
	v_mov_b32_e32 v17, v0
	v_mov_b32_e32 v18, v0
	v_mov_b32_e32 v19, v0
	v_mov_b32_e32 v36, v0
	v_mov_b32_e32 v37, v0
	v_mov_b32_e32 v38, v0
	v_mov_b32_e32 v39, v0
	v_mov_b32_e32 v40, v0
	v_mov_b32_e32 v41, v0
	v_mov_b32_e32 v42, v0
	v_mov_b32_e32 v43, v0
	v_mov_b32_e32 v120, v0
	v_mov_b32_e32 v121, v0
	v_mov_b32_e32 v122, v0
	v_mov_b32_e32 v123, v0
	v_mov_b32_e32 v124, v0
	v_mov_b32_e32 v125, v0
	v_mov_b32_e32 v126, v0
	v_mov_b32_e32 v127, v0
	v_mov_b32_e32 v128, v0
	v_mov_b32_e32 v129, v0
	v_mov_b32_e32 v130, v0
	v_mov_b32_e32 v131, v0
	v_mov_b32_e32 v132, v0
	v_mov_b32_e32 v133, v0
	v_mov_b32_e32 v134, v0
	v_mov_b32_e32 v135, v0
	v_mov_b32_e32 v28, v0
	v_mov_b32_e32 v29, v0
	v_mov_b32_e32 v30, v0
	v_mov_b32_e32 v31, v0
	v_mov_b32_e32 v32, v0
	v_mov_b32_e32 v33, v0
	v_mov_b32_e32 v34, v0
	v_mov_b32_e32 v35, v0
	s_branch .LBB0_1258
.Lg5_peel:
	ds_read_b128 v[138:141], v193
	ds_read_b128 v[142:145], v193 offset:1024
	ds_read_b128 v[146:149], v193 offset:2048
	ds_read_b128 v[150:153], v193 offset:3072
	ds_read_b128 v[154:157], v195
	ds_read_b128 v[158:161], v195 offset:1024
	ds_read_b128 v[162:165], v195 offset:2048
	ds_read_b128 v[182:185], v195 offset:3072
	s_add_u32 s58, s56, 0xfffc0080
	s_addc_u32 s59, s57, -1
	s_cmp_eq_u32 s86, 12
	s_cselect_b32 s61, s5, s59
	s_cselect_b32 s60, s37, s58
	s_cselect_b32 s59, s39, s85
	s_cselect_b32 s58, s55, s84
	v_lshl_add_u64 v[166:167], s[56:57], 0, v[178:179]
	s_add_i32 m0, s46, 0xc000
	ds_read_b128 v[198:201], v197
	ds_read_b128 v[202:205], v197 offset:1024
	ds_read_b128 v[210:213], v197 offset:2048
	ds_read_b128 v[214:217], v197 offset:3072
	ds_read_b128 v[218:221], v197 offset:4096
	ds_read_b128 v[222:225], v197 offset:5120
	ds_read_b128 v[230:233], v197 offset:6144
	ds_read_b128 v[234:237], v197 offset:7168
	global_load_lds_dwordx4 v[166:167], off
	v_lshl_add_u64 v[166:167], s[56:57], 0, v[180:181]
	s_add_i32 m0, s46, 0xe000
	s_nop 0
	global_load_lds_dwordx4 v[166:167], off
	s_waitcnt lgkmcnt(0)
	s_barrier
	s_setprio 1
	s_waitcnt lgkmcnt(0)
	v_mfma_f32_16x16x32_bf16 v[32:35], v[138:141], v[198:201], 0
	v_mfma_f32_16x16x32_bf16 v[28:31], v[146:149], v[198:201], 0
	v_mfma_f32_16x16x32_bf16 v[132:135], v[138:141], v[210:213], 0
	v_mfma_f32_16x16x32_bf16 v[128:131], v[146:149], v[210:213], 0
	v_mfma_f32_16x16x32_bf16 v[124:127], v[138:141], v[218:221], 0
	v_mfma_f32_16x16x32_bf16 v[120:123], v[146:149], v[218:221], 0
	v_mfma_f32_16x16x32_bf16 v[40:43], v[138:141], v[230:233], 0
	v_mfma_f32_16x16x32_bf16 v[36:39], v[146:149], v[230:233], 0
	v_mfma_f32_16x16x32_bf16 v[32:35], v[142:145], v[202:205], v[32:35]
	v_mfma_f32_16x16x32_bf16 v[28:31], v[150:153], v[202:205], v[28:31]
	v_mfma_f32_16x16x32_bf16 v[132:135], v[142:145], v[214:217], v[132:135]
	v_mfma_f32_16x16x32_bf16 v[128:131], v[150:153], v[214:217], v[128:131]
	v_mfma_f32_16x16x32_bf16 v[124:127], v[142:145], v[222:225], v[124:127]
	v_mfma_f32_16x16x32_bf16 v[120:123], v[150:153], v[222:225], v[120:123]
	v_mfma_f32_16x16x32_bf16 v[40:43], v[142:145], v[234:237], v[40:43]
	v_mfma_f32_16x16x32_bf16 v[36:39], v[150:153], v[234:237], v[36:39]
	s_setprio 0
	s_setprio 1
	v_mfma_f32_16x16x32_bf16 v[16:19], v[154:157], v[198:201], 0
	v_mfma_f32_16x16x32_bf16 v[12:15], v[162:165], v[198:201], 0
	v_mfma_f32_16x16x32_bf16 v[116:119], v[154:157], v[210:213], 0
	v_mfma_f32_16x16x32_bf16 v[112:115], v[162:165], v[210:213], 0
	v_mfma_f32_16x16x32_bf16 v[108:111], v[154:157], v[218:221], 0
	v_mfma_f32_16x16x32_bf16 v[104:107], v[162:165], v[218:221], 0
	v_mfma_f32_16x16x32_bf16 v[100:103], v[154:157], v[230:233], 0
	v_mfma_f32_16x16x32_bf16 v[96:99], v[162:165], v[230:233], 0
	v_mfma_f32_16x16x32_bf16 v[16:19], v[158:161], v[202:205], v[16:19]
	v_mfma_f32_16x16x32_bf16 v[12:15], v[182:185], v[202:205], v[12:15]
	v_mfma_f32_16x16x32_bf16 v[116:119], v[158:161], v[214:217], v[116:119]
	v_mfma_f32_16x16x32_bf16 v[112:115], v[182:185], v[214:217], v[112:115]
	v_mfma_f32_16x16x32_bf16 v[108:111], v[158:161], v[222:225], v[108:111]
	v_mfma_f32_16x16x32_bf16 v[104:107], v[182:185], v[222:225], v[104:107]
	v_mfma_f32_16x16x32_bf16 v[100:103], v[158:161], v[234:237], v[100:103]
	v_mfma_f32_16x16x32_bf16 v[96:99], v[182:185], v[234:237], v[96:99]
	s_setprio 0
	s_barrier
	s_add_i32 s87, s78, s35
	v_lshl_add_u64 v[166:167], s[58:59], 0, v[172:173]
	s_mov_b32 m0, s87
	ds_read_b128 v[198:201], v197 offset:16384
	ds_read_b128 v[202:205], v197 offset:17408
	ds_read_b128 v[210:213], v197 offset:18432
	ds_read_b128 v[214:217], v197 offset:19456
	ds_read_b128 v[218:221], v197 offset:20480
	ds_read_b128 v[222:225], v197 offset:21504
	ds_read_b128 v[230:233], v197 offset:22528
	ds_read_b128 v[234:237], v197 offset:23552
	global_load_lds_dwordx4 v[166:167], off
	s_add_i32 m0, s87, 0x2000
	s_add_u32 s90, s58, 0x40000
	v_lshl_add_u64 v[188:189], s[58:59], 0, v[168:169]
	s_addc_u32 s91, s59, 0
	s_add_i32 s87, s79, s35
	global_load_lds_dwordx4 v[188:189], off
	v_lshl_add_u64 v[226:227], s[90:91], 0, v[172:173]
	s_mov_b32 m0, s87
	v_lshl_add_u64 v[228:229], s[60:61], 0, v[170:171]
	global_load_lds_dwordx4 v[226:227], off
	v_lshl_add_u64 v[226:227], s[90:91], 0, v[168:169]
	s_add_i32 m0, s87, 0x2000
	s_nop 0
	global_load_lds_dwordx4 v[226:227], off
	v_lshl_add_u64 v[226:227], s[60:61], 0, v[174:175]
	s_mov_b32 m0, s46
	s_nop 0
	global_load_lds_dwordx4 v[226:227], off
	s_mov_b32 m0, s47
	s_nop 0
	global_load_lds_dwordx4 v[228:229], off
	s_waitcnt lgkmcnt(0)
	s_barrier
	s_setprio 1
	s_waitcnt lgkmcnt(0)
	v_mfma_f32_16x16x32_bf16 v[92:95], v[138:141], v[198:201], 0
	v_mfma_f32_16x16x32_bf16 v[88:91], v[146:149], v[198:201], 0
	v_mfma_f32_16x16x32_bf16 v[84:87], v[138:141], v[210:213], 0
	v_mfma_f32_16x16x32_bf16 v[80:83], v[146:149], v[210:213], 0
	v_mfma_f32_16x16x32_bf16 v[68:71], v[138:141], v[218:221], 0
	v_mfma_f32_16x16x32_bf16 v[64:67], v[146:149], v[218:221], 0
	v_mfma_f32_16x16x32_bf16 v[24:27], v[138:141], v[230:233], 0
	v_mfma_f32_16x16x32_bf16 v[20:23], v[146:149], v[230:233], 0
	v_mfma_f32_16x16x32_bf16 v[92:95], v[142:145], v[202:205], v[92:95]
	v_mfma_f32_16x16x32_bf16 v[88:91], v[150:153], v[202:205], v[88:91]
	v_mfma_f32_16x16x32_bf16 v[84:87], v[142:145], v[214:217], v[84:87]
	v_mfma_f32_16x16x32_bf16 v[80:83], v[150:153], v[214:217], v[80:83]
	v_mfma_f32_16x16x32_bf16 v[68:71], v[142:145], v[222:225], v[68:71]
	v_mfma_f32_16x16x32_bf16 v[64:67], v[150:153], v[222:225], v[64:67]
	v_mfma_f32_16x16x32_bf16 v[24:27], v[142:145], v[234:237], v[24:27]
	v_mfma_f32_16x16x32_bf16 v[20:23], v[150:153], v[234:237], v[20:23]
	s_setprio 0
	s_setprio 1
	v_mfma_f32_16x16x32_bf16 v[76:79], v[154:157], v[198:201], 0
	v_mfma_f32_16x16x32_bf16 v[72:75], v[162:165], v[198:201], 0
	v_mfma_f32_16x16x32_bf16 v[60:63], v[154:157], v[210:213], 0
	v_mfma_f32_16x16x32_bf16 v[56:59], v[162:165], v[210:213], 0
	v_mfma_f32_16x16x32_bf16 v[52:55], v[154:157], v[218:221], 0
	v_mfma_f32_16x16x32_bf16 v[48:51], v[162:165], v[218:221], 0
	v_mfma_f32_16x16x32_bf16 v[44:47], v[154:157], v[230:233], 0
	v_mfma_f32_16x16x32_bf16 v[0:3], v[162:165], v[230:233], 0
	v_mfma_f32_16x16x32_bf16 v[76:79], v[158:161], v[202:205], v[76:79]
	v_mfma_f32_16x16x32_bf16 v[72:75], v[182:185], v[202:205], v[72:75]
	v_mfma_f32_16x16x32_bf16 v[60:63], v[158:161], v[214:217], v[60:63]
	v_mfma_f32_16x16x32_bf16 v[56:59], v[182:185], v[214:217], v[56:59]
	v_mfma_f32_16x16x32_bf16 v[52:55], v[158:161], v[222:225], v[52:55]
	v_mfma_f32_16x16x32_bf16 v[48:51], v[182:185], v[222:225], v[48:51]
	v_mfma_f32_16x16x32_bf16 v[44:47], v[158:161], v[234:237], v[44:47]
	v_mfma_f32_16x16x32_bf16 v[0:3], v[182:185], v[234:237], v[0:3]
	s_setprio 0
	s_barrier
	s_branch .Lg5_mid

.Lg5_mid:
	s_add_i32 s87, 0, 0x18000
	v_add_u32_e32 v137, s87, v187
	s_add_i32 s90, 0, 0x1c000
	ds_read_b128 v[138:141], v137
	ds_read_b128 v[142:145], v137 offset:1024
	ds_read_b128 v[146:149], v137 offset:2048
	ds_read_b128 v[150:153], v137 offset:3072
	v_add_u32_e32 v137, s90, v187
	ds_read_b128 v[154:157], v137
	ds_read_b128 v[158:161], v137 offset:1024
	ds_read_b128 v[162:165], v137 offset:2048
	ds_read_b128 v[182:185], v137 offset:3072
	s_add_u32 s60, s60, 0x40000
	s_addc_u32 s61, s61, 0
	s_mov_b32 m0, s62
	v_lshl_add_u64 v[238:239], s[60:61], 0, v[174:175]
	ds_read_b128 v[198:201], v197 offset:32768
	ds_read_b128 v[202:205], v197 offset:33792
	ds_read_b128 v[210:213], v197 offset:34816
	ds_read_b128 v[214:217], v197 offset:35840
	ds_read_b128 v[218:221], v197 offset:36864
	ds_read_b128 v[222:225], v197 offset:37888
	ds_read_b128 v[230:233], v197 offset:38912
	ds_read_b128 v[234:237], v197 offset:39936
	global_load_lds_dwordx4 v[238:239], off
	v_lshl_add_u64 v[238:239], s[60:61], 0, v[170:171]
	s_mov_b32 m0, s63
	s_nop 0
	global_load_lds_dwordx4 v[238:239], off
	s_waitcnt vmcnt(8)
	s_waitcnt lgkmcnt(0)
	s_barrier
	s_setprio 1
	s_waitcnt lgkmcnt(0)
	v_mfma_f32_16x16x32_bf16 v[32:35], v[138:141], v[198:201], v[32:35]
	v_mfma_f32_16x16x32_bf16 v[28:31], v[146:149], v[198:201], v[28:31]
	v_mfma_f32_16x16x32_bf16 v[132:135], v[138:141], v[210:213], v[132:135]
	v_mfma_f32_16x16x32_bf16 v[128:131], v[146:149], v[210:213], v[128:131]
	v_mfma_f32_16x16x32_bf16 v[124:127], v[138:141], v[218:221], v[124:127]
	v_mfma_f32_16x16x32_bf16 v[120:123], v[146:149], v[218:221], v[120:123]
	v_mfma_f32_16x16x32_bf16 v[40:43], v[138:141], v[230:233], v[40:43]
	v_mfma_f32_16x16x32_bf16 v[36:39], v[146:149], v[230:233], v[36:39]
	v_mfma_f32_16x16x32_bf16 v[32:35], v[142:145], v[202:205], v[32:35]
	v_mfma_f32_16x16x32_bf16 v[28:31], v[150:153], v[202:205], v[28:31]
	v_mfma_f32_16x16x32_bf16 v[132:135], v[142:145], v[214:217], v[132:135]
	v_mfma_f32_16x16x32_bf16 v[128:131], v[150:153], v[214:217], v[128:131]
	v_mfma_f32_16x16x32_bf16 v[124:127], v[142:145], v[222:225], v[124:127]
	v_mfma_f32_16x16x32_bf16 v[120:123], v[150:153], v[222:225], v[120:123]
	v_mfma_f32_16x16x32_bf16 v[40:43], v[142:145], v[234:237], v[40:43]
	v_mfma_f32_16x16x32_bf16 v[36:39], v[150:153], v[234:237], v[36:39]
	s_setprio 0
	s_setprio 1
	v_mfma_f32_16x16x32_bf16 v[16:19], v[154:157], v[198:201], v[16:19]
	v_mfma_f32_16x16x32_bf16 v[12:15], v[162:165], v[198:201], v[12:15]
	v_mfma_f32_16x16x32_bf16 v[116:119], v[154:157], v[210:213], v[116:119]
	v_mfma_f32_16x16x32_bf16 v[112:115], v[162:165], v[210:213], v[112:115]
	v_mfma_f32_16x16x32_bf16 v[108:111], v[154:157], v[218:221], v[108:111]
	v_mfma_f32_16x16x32_bf16 v[104:107], v[162:165], v[218:221], v[104:107]
	v_mfma_f32_16x16x32_bf16 v[100:103], v[154:157], v[230:233], v[100:103]
	v_mfma_f32_16x16x32_bf16 v[96:99], v[162:165], v[230:233], v[96:99]
	v_mfma_f32_16x16x32_bf16 v[16:19], v[158:161], v[202:205], v[16:19]
	v_mfma_f32_16x16x32_bf16 v[12:15], v[182:185], v[202:205], v[12:15]
	v_mfma_f32_16x16x32_bf16 v[116:119], v[158:161], v[214:217], v[116:119]
	v_mfma_f32_16x16x32_bf16 v[112:115], v[182:185], v[214:217], v[112:115]
	v_mfma_f32_16x16x32_bf16 v[108:111], v[158:161], v[222:225], v[108:111]
	v_mfma_f32_16x16x32_bf16 v[104:107], v[182:185], v[222:225], v[104:107]
	v_mfma_f32_16x16x32_bf16 v[100:103], v[158:161], v[234:237], v[100:103]
	v_mfma_f32_16x16x32_bf16 v[96:99], v[182:185], v[234:237], v[96:99]
	s_setprio 0
	s_barrier
	s_add_i32 s60, s87, s35
	v_lshl_add_u64 v[166:167], v[166:167], 0, s[14:15]
	s_mov_b32 m0, s60
	ds_read_b128 v[198:201], v197 offset:49152
	ds_read_b128 v[202:205], v197 offset:50176
	ds_read_b128 v[210:213], v197 offset:51200
	ds_read_b128 v[214:217], v197 offset:52224
	ds_read_b128 v[218:221], v197 offset:53248
	ds_read_b128 v[222:225], v197 offset:54272
	ds_read_b128 v[230:233], v197 offset:55296
	ds_read_b128 v[234:237], v197 offset:56320
	global_load_lds_dwordx4 v[166:167], off
	s_add_i32 m0, s60, 0x2000
	s_add_u32 s58, s58, 0x40080
	v_lshl_add_u64 v[166:167], v[188:189], 0, s[14:15]
	s_addc_u32 s59, s59, 0
	s_add_i32 s60, s90, s35
	global_load_lds_dwordx4 v[166:167], off
	v_lshl_add_u64 v[166:167], s[58:59], 0, v[172:173]
	s_mov_b32 m0, s60
	s_nop 0
	global_load_lds_dwordx4 v[166:167], off
	v_lshl_add_u64 v[166:167], s[58:59], 0, v[168:169]
	s_add_i32 m0, s60, 0x2000
	s_nop 0
	global_load_lds_dwordx4 v[166:167], off
	v_lshl_add_u64 v[166:167], v[226:227], 0, s[14:15]
	s_mov_b32 m0, s67
	s_nop 0
	global_load_lds_dwordx4 v[166:167], off
	v_lshl_add_u64 v[166:167], v[228:229], 0, s[14:15]
	s_mov_b32 m0, s68
	s_nop 0
	global_load_lds_dwordx4 v[166:167], off
	s_waitcnt vmcnt(8)
	s_waitcnt lgkmcnt(0)
	s_barrier
	s_setprio 1
	s_waitcnt lgkmcnt(0)
	v_mfma_f32_16x16x32_bf16 v[92:95], v[138:141], v[198:201], v[92:95]
	v_mfma_f32_16x16x32_bf16 v[88:91], v[146:149], v[198:201], v[88:91]
	v_mfma_f32_16x16x32_bf16 v[84:87], v[138:141], v[210:213], v[84:87]
	v_mfma_f32_16x16x32_bf16 v[80:83], v[146:149], v[210:213], v[80:83]
	v_mfma_f32_16x16x32_bf16 v[68:71], v[138:141], v[218:221], v[68:71]
	v_mfma_f32_16x16x32_bf16 v[64:67], v[146:149], v[218:221], v[64:67]
	v_mfma_f32_16x16x32_bf16 v[24:27], v[138:141], v[230:233], v[24:27]
	v_mfma_f32_16x16x32_bf16 v[20:23], v[146:149], v[230:233], v[20:23]
	v_mfma_f32_16x16x32_bf16 v[92:95], v[142:145], v[202:205], v[92:95]
	v_mfma_f32_16x16x32_bf16 v[88:91], v[150:153], v[202:205], v[88:91]
	v_mfma_f32_16x16x32_bf16 v[84:87], v[142:145], v[214:217], v[84:87]
	v_mfma_f32_16x16x32_bf16 v[80:83], v[150:153], v[214:217], v[80:83]
	v_mfma_f32_16x16x32_bf16 v[68:71], v[142:145], v[222:225], v[68:71]
	v_mfma_f32_16x16x32_bf16 v[64:67], v[150:153], v[222:225], v[64:67]
	v_mfma_f32_16x16x32_bf16 v[24:27], v[142:145], v[234:237], v[24:27]
	v_mfma_f32_16x16x32_bf16 v[20:23], v[150:153], v[234:237], v[20:23]
	s_setprio 0
	s_setprio 1
	v_mfma_f32_16x16x32_bf16 v[76:79], v[154:157], v[198:201], v[76:79]
	v_mfma_f32_16x16x32_bf16 v[72:75], v[162:165], v[198:201], v[72:75]
	v_mfma_f32_16x16x32_bf16 v[60:63], v[154:157], v[210:213], v[60:63]
	v_mfma_f32_16x16x32_bf16 v[56:59], v[162:165], v[210:213], v[56:59]
	v_mfma_f32_16x16x32_bf16 v[52:55], v[154:157], v[218:221], v[52:55]
	v_mfma_f32_16x16x32_bf16 v[48:51], v[162:165], v[218:221], v[48:51]
	v_mfma_f32_16x16x32_bf16 v[44:47], v[154:157], v[230:233], v[44:47]
	v_mfma_f32_16x16x32_bf16 v[0:3], v[162:165], v[230:233], v[0:3]
	v_mfma_f32_16x16x32_bf16 v[76:79], v[158:161], v[202:205], v[76:79]
	v_mfma_f32_16x16x32_bf16 v[72:75], v[182:185], v[202:205], v[72:75]
	v_mfma_f32_16x16x32_bf16 v[60:63], v[158:161], v[214:217], v[60:63]
	v_mfma_f32_16x16x32_bf16 v[56:59], v[182:185], v[214:217], v[56:59]
	v_mfma_f32_16x16x32_bf16 v[52:55], v[158:161], v[222:225], v[52:55]
	v_mfma_f32_16x16x32_bf16 v[48:51], v[182:185], v[222:225], v[48:51]
	v_mfma_f32_16x16x32_bf16 v[44:47], v[158:161], v[234:237], v[44:47]
	v_mfma_f32_16x16x32_bf16 v[0:3], v[182:185], v[234:237], v[0:3]
	s_setprio 0
	s_barrier
	s_add_i32 s86, s86, 2
	s_add_u32 s56, s56, 0x100
	s_addc_u32 s57, s57, 0
	s_add_u32 s84, s84, 0x100
	s_addc_u32 s85, s85, 0
	s_cmp_gt_u32 s86, 13
	s_cbranch_scc0 .LBB0_1258
	s_and_b64 vcc, exec, s[16:17]
	s_cbranch_vccz .LBB0_1261
	s_barrier
